# scan-wave priority fix, attention: V loads hoisted + raw exp2 + key-tile rotation, GEMM1 epilogue rs0 loads hoisted
# speedup vs baseline: 1.0073x; 1.0073x over previous
.LBB0_625:
	s_ashr_i32 s18, s38, 12
	s_bfe_u32 s4, s38, 0x20007
	s_and_b32 s39, s38, 0x7f
	s_cmp_eq_u32 s18, 1
	s_cselect_b32 s2, 4, 16
	s_cselect_b32 s3, 2, 4
	s_cmpk_lt_u32 s38, 0x1000
	s_cselect_b32 s46, 1, s2
	s_cselect_b32 s19, 0, s3
	s_lshl_b32 s2, s18, 2
	s_or_b32 s47, s2, s4
	s_add_i32 s2, s47, 1
	v_cvt_f32_i32_e32 v0, s2
	s_xor_b32 s2, s19, 7
	s_lshr_b32 s49, s39, s2
	s_lshr_b32 s48, 0x80, s19
	v_mul_f32_e32 v0, 0xc1000000, v0
	v_div_scale_f32 v2, s[2:3], s15, s15, v0
	v_rcp_f32_e32 v3, v2
	s_add_i32 s48, s48, -1
	s_and_b32 s2, s48, s39
	s_lshl_b32 s39, s2, 5
	v_fma_f32 v4, -v2, v3, 1.0
	v_fmac_f32_e32 v3, v4, v3
	v_div_scale_f32 v4, vcc, v0, s15, v0
	v_mul_f32_e32 v5, v4, v3
	v_fma_f32 v6, -v2, v5, v4
	v_fmac_f32_e32 v5, v6, v3
	v_fma_f32 v2, -v2, v5, v4
	v_div_fmas_f32 v2, v2, v3, v5
	v_div_fixup_f32 v0, v2, s15, v0
	v_cmp_gt_f32_e32 vcc, s17, v0
	s_and_b64 s[2:3], vcc, exec
	s_cselect_b32 s48, 0xffffffc0, 0
	s_lshl_b32 s2, s38, 3
	s_and_b32 s2, s2, 0x7000
	v_or_b32_e32 v2, s39, v118
	s_or_b32 s49, s49, s2
	v_lshlrev_b32_e32 v2, s19, v2
	v_add_u32_e32 v92, s49, v2
	v_mad_u64_u32 v[2:3], s[2:3], v92, s20, v[82:83]
	s_lshl_b32 s2, s47, 6
	s_ashr_i32 s3, s2, 31
	s_lshl_b64 s[2:3], s[2:3], 1
	v_lshl_add_u64 v[94:95], v[2:3], 0, s[2:3]
	v_lshl_add_u64 v[2:3], v[94:95], 0, v[84:85]
	global_load_dwordx4 v[50:53], v[2:3], off
	global_load_dwordx4 v[54:57], v[2:3], off offset:32
	global_load_dwordx4 v[58:61], v[2:3], off offset:64
	global_load_dwordx4 v[62:65], v[2:3], off offset:96
	v_cndmask_b32_e32 v4, 0, v122, vcc
	v_add_f32_e32 v0, v0, v4
	v_exp_f32_e32 v0, v0
	s_mulk_i32 s49, 0x1200
	v_cvt_f32_ubyte0_e32 v2, s46
	s_add_u32 s46, s30, s49
	v_ldexp_f32 v0, v0, s48
	v_mul_f32_e32 v0, v0, v2
	s_addc_u32 s47, s31, 0
	v_mov_b32_e32 v14, v1
	v_mov_b32_e32 v15, v1
	v_mul_f32_e32 v97, 0x3fb8aa3b, v0
	s_add_u32 s2, s46, s2
	v_mov_b32_e32 v0, v1
	v_mov_b32_e32 v2, v1
	v_mov_b32_e32 v3, v1
	v_mov_b32_e32 v4, v1
	v_mov_b32_e32 v5, v1
	v_mov_b32_e32 v6, v1
	v_mov_b32_e32 v7, v1
	v_mov_b32_e32 v8, v1
	v_mov_b32_e32 v9, v1
	v_mov_b32_e32 v10, v1
	v_mov_b32_e32 v11, v1
	v_mov_b32_e32 v12, v1
	v_mov_b32_e32 v13, v1
	v_mov_b64_e32 v[32:33], v[14:15]
	s_addc_u32 s3, s47, s3
	v_mov_b64_e32 v[30:31], v[12:13]
	v_mov_b64_e32 v[28:29], v[10:11]
	v_mov_b64_e32 v[26:27], v[8:9]
	v_mov_b64_e32 v[24:25], v[6:7]
	v_mov_b64_e32 v[22:23], v[4:5]
	v_mov_b64_e32 v[20:21], v[2:3]
	v_mov_b64_e32 v[18:19], v[0:1]
	v_mov_b64_e32 v[16:17], v[14:15]
	v_mov_b32_e32 v93, v1
	v_lshl_add_u64 v[98:99], s[2:3], 0, v[86:87]
	v_lshl_add_u64 v[100:101], s[2:3], 0, v[84:85]
	v_mov_b32_e32 v102, v97
	v_mov_b32_e32 v103, v97
	v_or_b32_e32 v89, s39, v119
	v_add_u32_e32 v131, s39, v121
	v_mov_b32_e32 v133, 0xf149f2ca
	v_mov_b32_e32 v130, v1
	v_mov_b64_e32 v[14:15], v[12:13]
	v_mov_b64_e32 v[12:13], v[10:11]
	v_mov_b64_e32 v[10:11], v[8:9]
	v_mov_b64_e32 v[8:9], v[6:7]
	v_mov_b64_e32 v[6:7], v[4:5]
	v_mov_b64_e32 v[4:5], v[2:3]
	v_mov_b64_e32 v[2:3], v[0:1]
	s_lshr_b32 s54, s39, 5
	s_mul_i32 s55, s54, 0xcd
	s_lshr_b32 s55, s55, 10
	s_mul_i32 s55, s55, 5
	s_sub_i32 s54, s54, s55
	s_sub_i32 s54, 4, s54
	s_lshl_b32 s46, s54, 5
	v_subrev_u32_e32 v132, s46, v120
	s_mov_b32 s56, 5
	s_branch .LBB0_627
.LBB0_626:
	s_add_i32 s46, s46, 32
	v_subrev_u32_e32 v132, 32, v132
	s_cmpk_lg_i32 s46, 0xa0
	s_cbranch_scc1 .Lmy_attn_nowrap
	s_mov_b32 s46, 0
	v_add_u32_e32 v132, 0xa0, v132
.Lmy_attn_nowrap:
	s_sub_i32 s56, s56, 1
	s_cmp_eq_u32 s56, 0
	s_cbranch_scc1 .LBB0_629
.LBB0_627:
	s_add_i32 s2, s39, s46
	s_addk_i32 s2, 0xff80
	s_cmp_lt_i32 s2, 0
	s_cbranch_scc1 .LBB0_626
	v_add_u32_e32 v34, s46, v89
	v_add_u32_e32 v0, 0xffffff80, v34
	v_lshlrev_b64 v[38:39], s19, v[0:1]
	v_add_u32_e32 v0, 0xffffff88, v34
	v_lshlrev_b64 v[114:115], s19, v[0:1]
	v_add_u32_e32 v0, 0xffffff90, v34
	v_lshlrev_b64 v[150:151], s19, v[0:1]
	v_add_u32_e32 v0, 0xffffff98, v34
	v_lshlrev_b64 v[152:153], s19, v[0:1]
	v_add_u32_e32 v0, s46, v131
	v_lshlrev_b64 v[34:35], s19, v[0:1]
	v_mad_u64_u32 v[40:41], s[2:3], v34, s20, v[100:101]
	v_mad_u32_u24 v41, v35, s20, v41
	global_load_dwordx4 v[34:37], v[40:41], off offset:1536
	global_load_dwordx4 v[134:137], v[40:41], off offset:1568
	global_load_dwordx4 v[138:141], v[40:41], off offset:1600
	global_load_dwordx4 v[142:145], v[40:41], off offset:1632
	v_mad_u64_u32 v[40:41], s[2:3], v38, s20, v[98:99]
	v_mad_u32_u24 v41, v39, s20, v41
	v_and_b32_e32 v38, 64, v125
	global_load_dwordx4 v[146:149], v[40:41], off offset:3072
	v_add_u32_e32 v96, 64, v38
	v_add_u32_e32 v175, v132, v67
	v_add_u32_e32 v176, v132, v66
	v_cvt_f32_i32_e32 v157, v175
	v_cvt_f32_i32_e32 v156, v176
	v_add_u32_e32 v177, v69, v132
	v_add_u32_e32 v178, v68, v132
	v_cvt_f32_i32_e32 v159, v177
	v_cvt_f32_i32_e32 v158, v178
	v_xor_b32_e32 v0, 32, v125
	v_add_u32_e32 v168, v74, v132
	v_add_u32_e32 v179, v71, v132
	v_add_u32_e32 v180, v70, v132
	v_cvt_f32_i32_e32 v91, v168
	v_cvt_f32_i32_e32 v161, v179
	v_cvt_f32_i32_e32 v160, v180
	v_cmp_lt_i32_e32 vcc, v0, v96
	v_pk_mul_f32 v[156:157], v[102:103], v[156:157]
	v_pk_mul_f32 v[158:159], v[102:103], v[158:159]
	v_cndmask_b32_e32 v0, v125, v0, vcc
	v_cmp_gt_u32_e32 vcc, s21, v175
	v_lshlrev_b32_e32 v184, 2, v0
	v_add_u32_e32 v163, v75, v132
	v_mad_u64_u32 v[166:167], s[2:3], v114, s20, v[98:99]
	v_pk_mul_f32 v[160:161], v[102:103], v[160:161]
	v_mad_u32_u24 v167, v115, s20, v167
	v_mad_u64_u32 v[114:115], s[2:3], v150, s20, v[98:99]
	v_mad_u32_u24 v115, v151, s20, v115
	v_mad_u64_u32 v[150:151], s[2:3], v152, s20, v[98:99]
	v_mov_b32_e32 v155, v97
	v_add_u32_e32 v170, v76, v132
	v_mad_u32_u24 v151, v153, s20, v151
	global_load_dwordx4 v[186:189], v[166:167], off offset:3072
	global_load_dwordx4 v[190:193], v[114:115], off offset:3072
	global_load_dwordx4 v[194:197], v[150:151], off offset:3072
	v_mov_b32_e32 v117, v97
	v_add_u32_e32 v169, v77, v132
	v_mov_b32_e32 v113, v97
	v_add_u32_e32 v172, v78, v132
	v_mov_b32_e32 v111, v97
	v_add_u32_e32 v174, v80, v132
	v_mov_b32_e32 v109, v97
	v_add_u32_e32 v171, v79, v132
	v_mov_b32_e32 v107, v97
	v_add_u32_e32 v173, v81, v132
	v_mov_b32_e32 v105, v97
	v_add_u32_e32 v182, v73, v132
	v_add_u32_e32 v183, v72, v132
	v_cvt_f32_i32_e32 v165, v182
	v_cvt_f32_i32_e32 v164, v183
	s_waitcnt vmcnt(7)
	v_mfma_f32_32x32x16_bf16 v[34:49], v[34:37], v[50:53], 0
	s_waitcnt vmcnt(6)
	v_mfma_f32_32x32x16_bf16 v[34:49], v[134:137], v[54:57], v[34:49]
	s_waitcnt vmcnt(5)
	v_mfma_f32_32x32x16_bf16 v[34:49], v[138:141], v[58:61], v[34:49]
	s_waitcnt vmcnt(3)
	ds_write_b128 v123, v[146:149]
	s_waitcnt vmcnt(2)
	ds_write_b128 v123, v[186:189] offset:1024
	s_waitcnt vmcnt(1)
	ds_write_b128 v123, v[190:193] offset:2048
	s_waitcnt vmcnt(0)
	ds_write_b128 v123, v[194:197] offset:3072
	v_mfma_f32_32x32x16_bf16 v[34:49], v[142:145], v[62:65], v[34:49]
	s_waitcnt lgkmcnt(0)
	s_nop 11
	v_mov_b32_e32 v96, v42
	v_mov_b32_e32 v116, v43
	v_mov_b32_e32 v42, v34
	v_mov_b32_e32 v43, v36
	v_pk_fma_f32 v[42:43], v[42:43], s[16:17], v[156:157] op_sel_hi:[1,0,1] neg_lo:[0,0,1] neg_hi:[0,0,1]
	v_mov_b32_e32 v36, v35
	v_cndmask_b32_e32 v0, v126, v43, vcc
	v_cmp_gt_u32_e32 vcc, s21, v176
	v_mov_b32_e32 v110, v46
	v_pk_fma_f32 v[36:37], v[36:37], s[16:17], v[158:159] op_sel_hi:[1,0,1] neg_lo:[0,0,1] neg_hi:[0,0,1]
	v_cndmask_b32_e32 v46, v126, v42, vcc
	v_cmp_gt_u32_e32 vcc, s21, v177
	v_mov_b32_e32 v108, v47
	v_mov_b32_e32 v34, v38
	v_mov_b32_e32 v35, v40
	v_mov_b32_e32 v40, v39
	v_pk_mul_f32 v[38:39], v[96:97], v[90:91]
	v_cvt_f32_i32_e32 v91, v163
	v_cndmask_b32_e32 v47, v126, v37, vcc
	v_cmp_gt_u32_e32 vcc, s21, v178
	v_mov_b32_e32 v106, v48
	v_pk_fma_f32 v[34:35], v[34:35], s[16:17], v[160:161] op_sel_hi:[1,0,1] neg_lo:[0,0,1] neg_hi:[0,0,1]
	v_cndmask_b32_e32 v48, v126, v36, vcc
	v_cmp_gt_u32_e32 vcc, s21, v179
	v_mov_b32_e32 v104, v49
	v_mov_b32_e32 v154, v44
	v_cndmask_b32_e32 v49, v126, v35, vcc
	v_cmp_gt_u32_e32 vcc, s21, v180
	v_mov_b32_e32 v112, v45
	v_mov_b32_e32 v44, v38
	v_cndmask_b32_e32 v96, v126, v34, vcc
	v_max3_f32 v34, v46, s22, v48
	v_max3_f32 v114, v34, v0, v47
	v_pk_mul_f32 v[34:35], v[154:155], v[90:91]
	v_cvt_f32_i32_e32 v91, v170
	v_mov_b32_e32 v45, v34
	v_mov_b32_e32 v34, v39
	v_pk_add_f32 v[34:35], v[44:45], v[34:35] neg_lo:[0,1] neg_hi:[0,1]
	v_pk_mul_f32 v[36:37], v[116:117], v[90:91]
	v_cvt_f32_i32_e32 v91, v169
	v_cmp_gt_u32_e32 vcc, s21, v163
	v_mov_b32_e32 v38, v36
	s_nop 0
	v_cndmask_b32_e32 v44, v126, v35, vcc
	v_cmp_gt_u32_e32 vcc, s21, v168
	s_nop 1
	v_cndmask_b32_e32 v45, v126, v34, vcc
	v_pk_mul_f32 v[34:35], v[112:113], v[90:91]
	v_cvt_f32_i32_e32 v91, v172
	v_mov_b32_e32 v39, v34
	v_mov_b32_e32 v34, v37
	v_pk_add_f32 v[34:35], v[38:39], v[34:35] neg_lo:[0,1] neg_hi:[0,1]
	v_pk_mul_f32 v[36:37], v[110:111], v[90:91]
	v_cvt_f32_i32_e32 v91, v174
	v_cmp_gt_u32_e32 vcc, s21, v169
	v_pk_mul_f32 v[38:39], v[108:109], v[90:91]
	v_cvt_f32_i32_e32 v91, v171
	v_cndmask_b32_e32 v110, v126, v35, vcc
	v_cmp_gt_u32_e32 vcc, s21, v170
	v_pk_mul_f32 v[42:43], v[106:107], v[90:91]
	v_cvt_f32_i32_e32 v91, v173
	v_cndmask_b32_e32 v108, v126, v34, vcc
	v_mov_b32_e32 v34, v36
	v_mov_b32_e32 v35, v42
	v_mov_b32_e32 v42, v37
	v_pk_add_f32 v[34:35], v[34:35], v[42:43] neg_lo:[0,1] neg_hi:[0,1]
	v_cmp_gt_u32_e32 vcc, s21, v171
	v_mov_b32_e32 v36, v38
	s_nop 0
	v_cndmask_b32_e32 v42, v126, v35, vcc
	v_cmp_gt_u32_e32 vcc, s21, v172
	s_nop 1
	v_cndmask_b32_e32 v43, v126, v34, vcc
	v_pk_mul_f32 v[34:35], v[104:105], v[90:91]
	v_cmp_gt_u32_e32 vcc, s21, v173
	v_mov_b32_e32 v37, v34
	v_mov_b32_e32 v34, v39
	v_pk_add_f32 v[34:35], v[36:37], v[34:35] neg_lo:[0,1] neg_hi:[0,1]
	s_nop 0
	v_cndmask_b32_e32 v91, v126, v35, vcc
	v_cmp_gt_u32_e32 vcc, s21, v174
	s_nop 1
	v_cndmask_b32_e32 v104, v126, v34, vcc
	v_pk_mul_f32 v[34:35], v[102:103], v[164:165]
	v_cmp_gt_u32_e32 vcc, s21, v182
	v_pk_fma_f32 v[34:35], v[40:41], s[16:17], v[34:35] op_sel_hi:[1,0,1] neg_lo:[0,0,1] neg_hi:[0,0,1]
	s_nop 0
	v_cndmask_b32_e32 v105, v126, v35, vcc
	v_cmp_gt_u32_e32 vcc, s21, v183
	s_nop 1
	v_cndmask_b32_e32 v106, v126, v34, vcc
	v_max3_f32 v34, v114, v96, v106
	v_max3_f32 v34, v34, v49, v105
	v_max3_f32 v34, v34, v45, v108
	v_max3_f32 v34, v34, v44, v110
	v_max3_f32 v34, v34, v43, v104
	v_max3_f32 v34, v34, v42, v91
	ds_bpermute_b32 v35, v184, v34
	s_waitcnt lgkmcnt(0)
	v_max3_f32 v107, v133, v34, v35
	v_sub_f32_e32 v34, v46, v107
	v_sub_f32_e32 v111, v133, v107
	v_mov_b32_e32 v133, v107
	v_exp_f32_e32 v109, v34
	ds_read_b64_tr_b16 v[38:39], v124
	ds_read_b64_tr_b16 v[40:41], v124 offset:1024
	ds_read_b64_tr_b16 v[36:37], v124 offset:1088
	ds_read_b64_tr_b16 v[34:35], v124 offset:64
	v_sub_f32_e32 v112, v48, v107
	s_nop 1
	v_sub_f32_e32 v113, v0, v107
	v_exp_f32_e32 v112, v112
	s_nop 0
	v_exp_f32_e32 v113, v113
	v_cmp_lt_f32_e32 vcc, s23, v0
	v_sub_f32_e32 v0, v47, v107
	v_cmp_lt_f32_e64 s[2:3], s23, v46
	v_cndmask_b32_e32 v113, 0, v113, vcc
	s_nop 0
	v_cndmask_b32_e64 v46, 0, v109, s[2:3]
	s_nop 0
	v_exp_f32_e32 v0, v0
	v_cmp_lt_f32_e32 vcc, s23, v47
	s_nop 0
	s_nop 0
	v_cndmask_b32_e32 v47, 0, v0, vcc
	v_cmp_lt_f32_e32 vcc, s23, v48
	v_sub_f32_e32 v0, v96, v107
	s_nop 0
	v_cndmask_b32_e32 v48, 0, v112, vcc
	s_nop 1
	v_sub_f32_e32 v109, v49, v107
	v_exp_f32_e32 v0, v0
	s_nop 0
	v_exp_f32_e32 v109, v109
	v_cmp_lt_f32_e32 vcc, s23, v49
	s_nop 1
	v_cndmask_b32_e32 v49, 0, v109, vcc
	v_cmp_lt_f32_e32 vcc, s23, v96
	s_nop 1
	v_cndmask_b32_e32 v96, 0, v0, vcc
	v_sub_f32_e32 v0, v106, v107
	s_nop 1
	v_sub_f32_e32 v109, v105, v107
	v_exp_f32_e32 v0, v0
	s_nop 0
	v_exp_f32_e32 v109, v109
	v_cmp_lt_f32_e32 vcc, s23, v105
	s_nop 1
	v_cndmask_b32_e32 v105, 0, v109, vcc
	v_cmp_lt_f32_e32 vcc, s23, v106
	s_nop 1
	v_cndmask_b32_e32 v106, 0, v0, vcc
	v_sub_f32_e32 v0, v45, v107
	s_nop 1
	v_sub_f32_e32 v109, v44, v107
	v_exp_f32_e32 v0, v0
	s_nop 0
	v_exp_f32_e32 v109, v109
	v_cmp_lt_f32_e32 vcc, s23, v44
	s_nop 1
	v_cndmask_b32_e32 v109, 0, v109, vcc
	v_cmp_lt_f32_e32 vcc, s23, v45
	s_nop 1
	v_cndmask_b32_e32 v112, 0, v0, vcc
	v_sub_f32_e32 v0, v108, v107
	s_nop 1
	v_sub_f32_e32 v44, v110, v107
	v_exp_f32_e32 v0, v0
	s_nop 0
	v_exp_f32_e32 v44, v44
	v_cmp_lt_f32_e32 vcc, s23, v110
	s_nop 1
	v_cndmask_b32_e32 v110, 0, v44, vcc
	v_cmp_lt_f32_e32 vcc, s23, v108
	s_nop 1
	v_cndmask_b32_e32 v108, 0, v0, vcc
	v_sub_f32_e32 v0, v43, v107
	s_nop 1
	v_sub_f32_e32 v44, v42, v107
	v_exp_f32_e32 v0, v0
	s_nop 0
	v_exp_f32_e32 v44, v44
	v_cmp_lt_f32_e32 vcc, s23, v42
	v_bfe_u32 v45, v48, 16, 1
	s_nop 0
	v_cndmask_b32_e32 v114, 0, v44, vcc
	v_cmp_lt_f32_e32 vcc, s23, v43
	v_bfe_u32 v44, v47, 16, 1
	s_nop 0
	v_cndmask_b32_e32 v115, 0, v0, vcc
	v_sub_f32_e32 v0, v104, v107
	s_nop 1
	v_sub_f32_e32 v42, v91, v107
	v_exp_f32_e32 v0, v0
	s_nop 0
	v_exp_f32_e32 v42, v42
	v_cmp_lt_f32_e32 vcc, s23, v91
	v_bfe_u32 v43, v106, 16, 1
	v_add3_u32 v43, v106, v43, s28
	v_cndmask_b32_e32 v91, 0, v42, vcc
	v_cmp_lt_f32_e32 vcc, s23, v104
	s_nop 1
	v_cndmask_b32_e32 v104, 0, v0, vcc
	v_add_f32_e32 v0, v46, v48
	v_add_f32_e32 v0, v113, v0
	v_add_f32_e32 v0, v47, v0
	v_add_f32_e32 v0, v96, v0
	v_add_f32_e32 v0, v106, v0
	v_add_f32_e32 v0, v49, v0
	v_add_f32_e32 v0, v105, v0
	v_add_f32_e32 v0, v112, v0
	v_add_f32_e32 v0, v108, v0
	v_add_f32_e32 v0, v109, v0
	v_mov_b32_e32 v42, v111
	v_add_f32_e32 v0, v110, v0
	v_exp_f32_e32 v42, v42
	v_add_f32_e32 v0, v115, v0
	v_add_f32_e32 v0, v104, v0
	v_add_f32_e32 v111, v114, v0
	v_mov_b32_e32 v0, v42
	v_bfe_u32 v42, v105, 16, 1
	v_add3_u32 v48, v48, v45, s28
	v_add3_u32 v47, v47, v44, s28
	v_add3_u32 v42, v105, v42, s28
	v_bfe_u32 v44, v46, 16, 1
	v_bfe_u32 v45, v113, 16, 1
	v_bfe_u32 v105, v96, 16, 1
	v_bfe_u32 v106, v49, 16, 1
	v_add3_u32 v49, v49, v106, s28
	v_add3_u32 v96, v96, v105, s28
	v_add3_u32 v45, v113, v45, s28
	v_add3_u32 v44, v46, v44, s28
	v_lshrrev_b32_e32 v46, 16, v44
	v_lshrrev_b32_e32 v105, 16, v45
	v_lshrrev_b32_e32 v44, 16, v96
	v_lshrrev_b32_e32 v45, 16, v49
	v_pk_mul_f32 v[32:33], v[32:33], v[0:1] op_sel_hi:[1,0]
	v_pk_mul_f32 v[30:31], v[30:31], v[0:1] op_sel_hi:[1,0]
	v_pk_mul_f32 v[28:29], v[28:29], v[0:1] op_sel_hi:[1,0]
	v_pk_mul_f32 v[26:27], v[26:27], v[0:1] op_sel_hi:[1,0]
	v_pk_mul_f32 v[24:25], v[24:25], v[0:1] op_sel_hi:[1,0]
	v_pk_mul_f32 v[22:23], v[22:23], v[0:1] op_sel_hi:[1,0]
	v_pk_mul_f32 v[20:21], v[20:21], v[0:1] op_sel_hi:[1,0]
	v_pk_mul_f32 v[18:19], v[18:19], v[0:1] op_sel_hi:[1,0]
	v_pk_mul_f32 v[16:17], v[16:17], v[0:1] op_sel_hi:[1,0]
	v_and_or_b32 v45, v42, s29, v45
	v_and_or_b32 v44, v43, s29, v44
	v_and_or_b32 v43, v47, s29, v105
	v_and_or_b32 v42, v48, s29, v46
	v_pk_mul_f32 v[14:15], v[14:15], v[0:1] op_sel_hi:[1,0]
	v_pk_mul_f32 v[12:13], v[12:13], v[0:1] op_sel_hi:[1,0]
	v_pk_mul_f32 v[10:11], v[10:11], v[0:1] op_sel_hi:[1,0]
	v_pk_mul_f32 v[8:9], v[8:9], v[0:1] op_sel_hi:[1,0]
	v_pk_mul_f32 v[6:7], v[6:7], v[0:1] op_sel_hi:[1,0]
	v_pk_mul_f32 v[4:5], v[4:5], v[0:1] op_sel_hi:[1,0]
	v_pk_mul_f32 v[2:3], v[2:3], v[0:1] op_sel_hi:[1,0]
	s_waitcnt lgkmcnt(2)
	v_mfma_f32_32x32x16_bf16 v[18:33], v[38:41], v[42:45], v[18:33]
	s_waitcnt lgkmcnt(0)
	v_mfma_f32_32x32x16_bf16 v[2:17], v[34:37], v[42:45], v[2:17]
	v_bfe_u32 v34, v91, 16, 1
	v_bfe_u32 v35, v104, 16, 1
	v_bfe_u32 v36, v110, 16, 1
	v_bfe_u32 v37, v108, 16, 1
	v_add3_u32 v38, v108, v37, s28
	v_add3_u32 v39, v110, v36, s28
	v_add3_u32 v40, v104, v35, s28
	v_add3_u32 v41, v91, v34, s28
	v_bfe_u32 v34, v112, 16, 1
	v_bfe_u32 v35, v109, 16, 1
	v_bfe_u32 v36, v115, 16, 1
	v_bfe_u32 v37, v114, 16, 1
	v_add3_u32 v42, v114, v37, s28
	v_add3_u32 v43, v115, v36, s28
	v_add3_u32 v35, v109, v35, s28
	v_add3_u32 v34, v112, v34, s28
	v_lshrrev_b32_e32 v44, 16, v34
	v_lshrrev_b32_e32 v45, 16, v35
	ds_read_b64_tr_b16 v[34:35], v124 offset:2048
	ds_read_b64_tr_b16 v[36:37], v124 offset:3072
	v_lshrrev_b32_e32 v43, 16, v43
	v_lshrrev_b32_e32 v42, 16, v42
	v_and_or_b32 v41, v41, s29, v42
	v_and_or_b32 v40, v40, s29, v43
	v_and_or_b32 v39, v39, s29, v45
	v_and_or_b32 v38, v38, s29, v44
	ds_read_b64_tr_b16 v[44:45], v124 offset:3136
	ds_read_b64_tr_b16 v[42:43], v124 offset:2112
	s_waitcnt lgkmcnt(2)
	v_mfma_f32_32x32x16_bf16 v[18:33], v[34:37], v[38:41], v[18:33]
	v_add_f32_e32 v34, v91, v111
	ds_bpermute_b32 v35, v184, v34
	s_waitcnt lgkmcnt(0)
	s_waitcnt lgkmcnt(0)
	v_add_f32_e32 v34, v34, v35
	v_mfma_f32_32x32x16_bf16 v[2:17], v[42:45], v[38:41], v[2:17]
	v_fmac_f32_e32 v34, v130, v0
	v_mov_b32_e32 v130, v34
	s_branch .LBB0_626
